# adds: branch GEMM keeps one gate plane in 32 spare VGPRs across the K-loop: second boundary loads 8 instead of 16 gate quads, final gate multiply loads none
# speedup vs baseline: 1.0023x; 1.0009x over previous
; #define GAS __attribute__((address_space(1)))
;     __device__ __forceinline__ void mid(f32x4 (&acc)[2][2][4][2], const pg8::GUnit& u, int b, int wr, int wc, int fr, int fq) const {
;     ...
;         const GAS unsigned char* gp = (const GAS unsigned char*)P + (size_t)(u.pm * 256 + (wr * 4 + wc) * 32 + fq) * (INW * 2) + (GA * 2 + (b * 16 + u.pn) * 256 + fr * 16);
;         u32x4 gn[8], gd[8];
; #pragma unroll
;         for (int k = 0; k < 8; ++k) { const GAS unsigned char* q = gp + (size_t)(k * 4) * (INW * 2); gn[k] = *(const GAS u32x4*)q; gd[k] = *(const GAS u32x4*)(q + DM); }
;     __device__ __forceinline__ void operator()(const f32x4 (&acc)[2][2][4][2], const pg8::GUnit& u, int wr, int wc, int fr, int fq) const {
;     ...
;         const GAS unsigned char* gp = (const GAS unsigned char*)P + (size_t)(u.pm * 256 + (wr * 4 + wc) * 32 + fq) * (INW * 2) + (GA * 2 + (2 * 16 + u.pn) * 256 + fr * 16);
;         u32x4 g[8];
; #pragma unroll
;         for (int k = 0; k < 8; ++k) g[k] = *(const GAS u32x4*)(gp + (size_t)(k * 4) * (INW * 2));
.Lbr_mid1_load:
	s_cmpk_eq_i32 s89, 0xc00
	v_ashrrev_i32_e32 v2, 4, v0
	v_add_u32_e32 v2, s84, v2
	v_mad_i64_i32 v[2:3], s[8:9], v2, s93, v[200:201]
	s_cselect_b32 s8, 0, 0x1000
	v_lshlrev_b32_e32 v0, 4, v0
	s_add_i32 s8, s87, s8
	v_and_b32_e32 v0, 0xf0, v0
	v_or_b32_e32 v132, s8, v0
	v_ashrrev_i32_e32 v133, 31, v132
	v_lshl_add_u64 v[2:3], v[2:3], 0, v[132:133]
	v_add_co_u32_e32 v132, vcc, s35, v2
	s_nop 0
	v_addc_co_u32_e32 v133, vcc, 0, v3, vcc
	global_load_dwordx4 v[192:195], v[132:133], off
	s_mov_b32 s8, 0x31000
	v_add_co_u32_e32 v132, vcc, s8, v2
	s_mov_b32 s8, 0x61000
	s_nop 0
	v_addc_co_u32_e32 v133, vcc, 0, v3, vcc
	global_load_dwordx4 v[184:187], v[132:133], off
	v_add_co_u32_e32 v132, vcc, s8, v2
	s_mov_b32 s8, 0x91000
	s_nop 0
	v_addc_co_u32_e32 v133, vcc, 0, v3, vcc
	global_load_dwordx4 v[176:179], v[132:133], off
	v_add_co_u32_e32 v132, vcc, s8, v2
	s_mov_b32 s8, 0xc1000
	s_nop 0
	v_addc_co_u32_e32 v133, vcc, 0, v3, vcc
	global_load_dwordx4 v[168:171], v[132:133], off
	v_add_co_u32_e32 v132, vcc, s8, v2
	s_mov_b32 s8, 0xf1000
	s_nop 0
	v_addc_co_u32_e32 v133, vcc, 0, v3, vcc
	global_load_dwordx4 v[160:163], v[132:133], off
	v_add_co_u32_e32 v132, vcc, s8, v2
	s_mov_b32 s8, 0x121000
	s_nop 0
	v_addc_co_u32_e32 v133, vcc, 0, v3, vcc
	global_load_dwordx4 v[152:155], v[132:133], off
	v_add_co_u32_e32 v132, vcc, s8, v2
	s_mov_b32 s8, 0x151000
	s_nop 0
	v_addc_co_u32_e32 v133, vcc, 0, v3, vcc
	v_add_co_u32_e32 v2, vcc, s8, v2
	global_load_dwordx4 v[144:147], v[132:133], off
	v_addc_co_u32_e32 v3, vcc, 0, v3, vcc
	global_load_dwordx4 v[136:139], v[2:3], off
	v_mov_b32_e32 v188, v215
	v_mov_b32_e32 v189, v216
	v_mov_b32_e32 v190, v217
	v_mov_b32_e32 v191, v218
	v_mov_b32_e32 v180, v219
	v_mov_b32_e32 v181, v220
	v_mov_b32_e32 v182, v221
	v_mov_b32_e32 v183, v222
	v_mov_b32_e32 v172, v223
	v_mov_b32_e32 v173, v224
	v_mov_b32_e32 v174, v225
	v_mov_b32_e32 v175, v226
	v_mov_b32_e32 v164, v227
	v_mov_b32_e32 v165, v228
	v_mov_b32_e32 v166, v229
	v_mov_b32_e32 v167, v230
	v_mov_b32_e32 v156, v231
	v_mov_b32_e32 v157, v232
	v_mov_b32_e32 v158, v233
	v_mov_b32_e32 v159, v234
	v_mov_b32_e32 v148, v235
	v_mov_b32_e32 v149, v236
	v_mov_b32_e32 v150, v237
	v_mov_b32_e32 v151, v238
	v_mov_b32_e32 v140, v239
	v_mov_b32_e32 v141, v240
	v_mov_b32_e32 v142, v241
	v_mov_b32_e32 v143, v242
	v_mov_b32_e32 v132, v243
	v_mov_b32_e32 v133, v245
	v_mov_b32_e32 v134, v246
	v_mov_b32_e32 v135, v247
	s_branch .Lbr_mid_wait
.LBB0_777:
	v_mbcnt_lo_u32_b32 v0, -1, 0
	v_mbcnt_hi_u32_b32 v0, -1, v0
	s_add_i32 s83, s83, s3
	v_and_b32_e32 v134, 15, v0
	v_ashrrev_i32_e32 v0, 4, v0
	s_or_b32 s8, s82, s1
	s_add_i32 s82, s82, 0x8000
	v_or_b32_e32 v2, s83, v134
	v_lshl_add_u32 v164, v0, 3, s8
	v_add_u32_e32 v0, s84, v0
	v_lshl_or_b32 v134, v134, 4, s82
	v_mad_i64_i32 v[132:133], s[8:9], v0, s93, v[200:201]
	v_ashrrev_i32_e32 v135, 31, v134
	v_lshl_add_u64 v[136:137], v[132:133], 0, v[134:135]
	v_add_co_u32_e32 v132, vcc, s48, v136
	s_mov_b32 s9, 0x60000
	s_nop 0
	v_addc_co_u32_e32 v133, vcc, 0, v137, vcc
	v_add_co_u32_e32 v132, vcc, s9, v136
	s_mov_b32 s8, 0x90000
	s_nop 0
	v_addc_co_u32_e32 v133, vcc, 0, v137, vcc
	v_add_co_u32_e32 v132, vcc, s8, v136
	v_ashrrev_i32_e32 v3, 31, v2
	s_nop 0
	v_addc_co_u32_e32 v133, vcc, 0, v137, vcc
	s_mov_b32 s8, 0xc0000
	v_lshlrev_b64 v[2:3], 13, v[2:3]
	v_add_co_u32_e32 v132, vcc, s8, v136
	v_ashrrev_i32_e32 v165, 31, v164
	s_nop 0
	v_addc_co_u32_e32 v133, vcc, 0, v137, vcc
	v_lshl_add_u64 v[2:3], v[198:199], 0, v[2:3]
	v_lshl_add_u64 v[2:3], v[164:165], 1, v[2:3]
	s_mov_b32 s8, 0xf0000
	v_add_co_u32_e32 v132, vcc, s8, v136
	s_mov_b32 s10, 0x120000
	s_nop 0
	v_addc_co_u32_e32 v133, vcc, 0, v137, vcc
	v_add_co_u32_e32 v132, vcc, s10, v136
	s_mov_b32 s8, 0x150000
	s_nop 0
	v_addc_co_u32_e32 v133, vcc, 0, v137, vcc
	v_add_co_u32_e32 v136, vcc, s8, v136
	s_nop 0
	v_addc_co_u32_e32 v137, vcc, 0, v137, vcc
	s_mov_b32 s8, 0x40000
	s_mov_b32 s26, 0x60000
	s_mov_b32 s27, 0x120000
	s_mov_b32 s86, s46
	v_mov_b32_e32 v160, v215
	v_mov_b32_e32 v161, v216
	v_mov_b32_e32 v162, v217
	v_mov_b32_e32 v163, v218
	v_mov_b32_e32 v156, v219
	v_mov_b32_e32 v157, v220
	v_mov_b32_e32 v158, v221
	v_mov_b32_e32 v159, v222
	v_mov_b32_e32 v152, v223
	v_mov_b32_e32 v153, v224
	v_mov_b32_e32 v154, v225
	v_mov_b32_e32 v155, v226
	v_mov_b32_e32 v148, v227
	v_mov_b32_e32 v149, v228
	v_mov_b32_e32 v150, v229
	v_mov_b32_e32 v151, v230
	v_mov_b32_e32 v144, v231
	v_mov_b32_e32 v145, v232
	v_mov_b32_e32 v146, v233
	v_mov_b32_e32 v147, v234
	v_mov_b32_e32 v140, v235
	v_mov_b32_e32 v141, v236
	v_mov_b32_e32 v142, v237
	v_mov_b32_e32 v143, v238
	v_mov_b32_e32 v132, v239
	v_mov_b32_e32 v133, v240
	v_mov_b32_e32 v134, v241
	v_mov_b32_e32 v135, v242
	v_mov_b32_e32 v136, v243
	v_mov_b32_e32 v137, v245
	v_mov_b32_e32 v138, v246
	v_mov_b32_e32 v139, v247
	s_waitcnt vmcnt(0)
; #define GAS __attribute__((address_space(1)))
; __device__ __forceinline__ unsigned cvt_pk_bf16(float lo, float hi) { const f32x2_t_ v = {lo, hi}; const bf16x2_t_ b = __builtin_convertvector(v, bf16x2_t_); return __builtin_bit_cast(unsigned, b); }
; __device__ __forceinline__ void gate_mul4(f32x4& v, unsigned g) { const float s = 1.0f / 255.0f; v[0] *= ub0(g) * s; v[1] *= ub1(g) * s; v[2] *= ub2(g) * s; v[3] *= ub3(g) * s; }
;     __device__ __forceinline__ void operator()(const f32x4 (&acc)[2][2][4][2], const pg8::GUnit& u, int wr, int wc, int fr, int fq) const {
;     ...
;         for (int k = 0; k < 8; ++k) { const int ai = k >> 2, m = k & 3;
; #pragma unroll
;             for (int bj = 0; bj < 2; ++bj) { f32x4 v0 = acc[ai][bj][m][0], v1 = acc[ai][bj][m][1];
;                 gate_mul4(v0, bj ? g[k].z : g[k].x); gate_mul4(v1, bj ? g[k].w : g[k].y);
;                 u32x4 w; w.x = cvt_pk_bf16(v0[0], v0[1]); w.y = cvt_pk_bf16(v0[2], v0[3]); w.z = cvt_pk_bf16(v1[0], v1[1]); w.w = cvt_pk_bf16(v1[2], v1[3]);
;                 *(GAS u32x4*)(mp0 + (size_t)(ai * 128 + m * 16) * DM + bj * 128) = w; } }
	v_cvt_f32_ubyte1_e32 v165, v160
	v_cvt_f32_ubyte0_e32 v164, v160
	v_pk_mul_f32 v[164:165], v[164:165], s[6:7] op_sel_hi:[1,0]
	s_nop 0
	v_pk_mul_f32 v[128:129], v[128:129], v[164:165]
	v_cvt_f32_ubyte3_e32 v165, v160
	v_cvt_f32_ubyte2_e32 v164, v160
	v_pk_mul_f32 v[164:165], v[164:165], s[6:7] op_sel_hi:[1,0]
	s_nop 0
	v_pk_mul_f32 v[130:131], v[130:131], v[164:165]
	v_cvt_f32_ubyte1_e32 v165, v161
	v_cvt_f32_ubyte0_e32 v164, v161
	v_pk_mul_f32 v[164:165], v[164:165], s[6:7] op_sel_hi:[1,0]
	s_nop 0
	v_pk_mul_f32 v[164:165], v[124:125], v[164:165]
	v_cvt_f32_ubyte3_e32 v125, v161
	v_cvt_f32_ubyte2_e32 v124, v161
	v_pk_mul_f32 v[124:125], v[124:125], s[6:7] op_sel_hi:[1,0]
	s_nop 0
	v_pk_mul_f32 v[160:161], v[126:127], v[124:125]
	v_cvt_pk_bf16_f32 v124, v128, v129
	v_cvt_pk_bf16_f32 v125, v130, v131
	v_cvt_pk_bf16_f32 v126, v164, v165
	v_cvt_pk_bf16_f32 v127, v160, v161
	global_store_dwordx4 v[2:3], v[124:127], off
	s_nop 1
	v_cvt_f32_ubyte1_e32 v125, v162
	v_cvt_f32_ubyte0_e32 v124, v162
	v_pk_mul_f32 v[124:125], v[124:125], s[6:7] op_sel_hi:[1,0]
	s_nop 0
	v_pk_mul_f32 v[120:121], v[120:121], v[124:125]
	v_cvt_f32_ubyte3_e32 v125, v162
	v_cvt_f32_ubyte2_e32 v124, v162
	v_pk_mul_f32 v[124:125], v[124:125], s[6:7] op_sel_hi:[1,0]
	s_nop 0
	v_pk_mul_f32 v[122:123], v[122:123], v[124:125]
	v_cvt_f32_ubyte1_e32 v125, v163
	v_cvt_f32_ubyte0_e32 v124, v163
	v_pk_mul_f32 v[124:125], v[124:125], s[6:7] op_sel_hi:[1,0]
	s_nop 0
	v_pk_mul_f32 v[124:125], v[116:117], v[124:125]
	v_cvt_f32_ubyte3_e32 v117, v163
	v_cvt_f32_ubyte2_e32 v116, v163
	v_pk_mul_f32 v[116:117], v[116:117], s[6:7] op_sel_hi:[1,0]
	s_nop 0
	v_pk_mul_f32 v[126:127], v[118:119], v[116:117]
	v_cvt_pk_bf16_f32 v116, v120, v121
	v_cvt_pk_bf16_f32 v117, v122, v123
	v_cvt_pk_bf16_f32 v118, v124, v125
	v_cvt_pk_bf16_f32 v119, v126, v127
	global_store_dwordx4 v[2:3], v[116:119], off offset:256
	s_nop 1
	v_cvt_f32_ubyte1_e32 v117, v156
	v_cvt_f32_ubyte0_e32 v116, v156
	v_pk_mul_f32 v[116:117], v[116:117], s[6:7] op_sel_hi:[1,0]
	s_nop 0
	v_pk_mul_f32 v[112:113], v[112:113], v[116:117]
	v_cvt_f32_ubyte3_e32 v117, v156
	v_cvt_f32_ubyte2_e32 v116, v156
	v_pk_mul_f32 v[116:117], v[116:117], s[6:7] op_sel_hi:[1,0]
	s_nop 0
	v_pk_mul_f32 v[114:115], v[114:115], v[116:117]
	v_cvt_f32_ubyte1_e32 v117, v157
	v_cvt_f32_ubyte0_e32 v116, v157
	v_pk_mul_f32 v[116:117], v[116:117], s[6:7] op_sel_hi:[1,0]
	s_nop 0
	v_pk_mul_f32 v[116:117], v[108:109], v[116:117]
	v_cvt_f32_ubyte3_e32 v109, v157
	v_cvt_f32_ubyte2_e32 v108, v157
	v_pk_mul_f32 v[108:109], v[108:109], s[6:7] op_sel_hi:[1,0]
	s_nop 0
	v_pk_mul_f32 v[118:119], v[110:111], v[108:109]
	v_cvt_pk_bf16_f32 v108, v112, v113
	v_add_co_u32_e32 v112, vcc, s29, v2
	v_cvt_pk_bf16_f32 v109, v114, v115
	v_cvt_pk_bf16_f32 v110, v116, v117
	v_cvt_pk_bf16_f32 v111, v118, v119
	v_addc_co_u32_e32 v113, vcc, 0, v3, vcc
	global_store_dwordx4 v[112:113], v[108:111], off
	s_nop 1
	v_cvt_f32_ubyte1_e32 v109, v158
	v_cvt_f32_ubyte0_e32 v108, v158
	v_pk_mul_f32 v[108:109], v[108:109], s[6:7] op_sel_hi:[1,0]
	s_nop 0
	v_pk_mul_f32 v[104:105], v[104:105], v[108:109]
	v_cvt_f32_ubyte3_e32 v109, v158
	v_cvt_f32_ubyte2_e32 v108, v158
	v_pk_mul_f32 v[108:109], v[108:109], s[6:7] op_sel_hi:[1,0]
	s_nop 0
	v_pk_mul_f32 v[106:107], v[106:107], v[108:109]
	v_cvt_f32_ubyte1_e32 v109, v159
	v_cvt_f32_ubyte0_e32 v108, v159
	v_pk_mul_f32 v[108:109], v[108:109], s[6:7] op_sel_hi:[1,0]
	s_nop 0
	v_pk_mul_f32 v[108:109], v[100:101], v[108:109]
	v_cvt_f32_ubyte3_e32 v101, v159
	v_cvt_f32_ubyte2_e32 v100, v159
	v_pk_mul_f32 v[100:101], v[100:101], s[6:7] op_sel_hi:[1,0]
	s_nop 0
	v_pk_mul_f32 v[110:111], v[102:103], v[100:101]
	v_cvt_pk_bf16_f32 v100, v104, v105
	v_cvt_pk_bf16_f32 v101, v106, v107
	v_cvt_pk_bf16_f32 v102, v108, v109
	v_cvt_pk_bf16_f32 v103, v110, v111
	global_store_dwordx4 v[112:113], v[100:103], off offset:256
	s_nop 1
	v_cvt_f32_ubyte1_e32 v101, v152
	v_cvt_f32_ubyte0_e32 v100, v152
	v_pk_mul_f32 v[100:101], v[100:101], s[6:7] op_sel_hi:[1,0]
	s_nop 0
	v_pk_mul_f32 v[96:97], v[96:97], v[100:101]
	v_cvt_f32_ubyte3_e32 v101, v152
	v_cvt_f32_ubyte2_e32 v100, v152
	v_pk_mul_f32 v[100:101], v[100:101], s[6:7] op_sel_hi:[1,0]
	s_nop 0
	v_pk_mul_f32 v[98:99], v[98:99], v[100:101]
	v_cvt_f32_ubyte1_e32 v101, v153
	v_cvt_f32_ubyte0_e32 v100, v153
	v_pk_mul_f32 v[100:101], v[100:101], s[6:7] op_sel_hi:[1,0]
	s_nop 0
	v_pk_mul_f32 v[100:101], v[92:93], v[100:101]
	v_cvt_f32_ubyte3_e32 v93, v153
	v_cvt_f32_ubyte2_e32 v92, v153
	v_pk_mul_f32 v[92:93], v[92:93], s[6:7] op_sel_hi:[1,0]
	s_nop 0
	v_pk_mul_f32 v[102:103], v[94:95], v[92:93]
	v_cvt_pk_bf16_f32 v92, v96, v97
	v_add_co_u32_e32 v96, vcc, s8, v2
	v_cvt_pk_bf16_f32 v93, v98, v99
	v_cvt_pk_bf16_f32 v94, v100, v101
	v_cvt_pk_bf16_f32 v95, v102, v103
	v_addc_co_u32_e32 v97, vcc, 0, v3, vcc
	global_store_dwordx4 v[96:97], v[92:95], off
	s_mov_b32 s8, 0x100000
	s_nop 0
	v_cvt_f32_ubyte1_e32 v93, v154
	v_cvt_f32_ubyte0_e32 v92, v154
	v_pk_mul_f32 v[92:93], v[92:93], s[6:7] op_sel_hi:[1,0]
	s_nop 0
	v_pk_mul_f32 v[88:89], v[88:89], v[92:93]
	v_cvt_f32_ubyte3_e32 v93, v154
	v_cvt_f32_ubyte2_e32 v92, v154
	v_pk_mul_f32 v[92:93], v[92:93], s[6:7] op_sel_hi:[1,0]
	s_nop 0
	v_pk_mul_f32 v[90:91], v[90:91], v[92:93]
	v_cvt_f32_ubyte1_e32 v93, v155
	v_cvt_f32_ubyte0_e32 v92, v155
	v_pk_mul_f32 v[92:93], v[92:93], s[6:7] op_sel_hi:[1,0]
	s_nop 0
	v_pk_mul_f32 v[92:93], v[84:85], v[92:93]
	v_cvt_f32_ubyte3_e32 v85, v155
	v_cvt_f32_ubyte2_e32 v84, v155
	v_pk_mul_f32 v[84:85], v[84:85], s[6:7] op_sel_hi:[1,0]
	s_nop 0
	v_pk_mul_f32 v[94:95], v[86:87], v[84:85]
	v_cvt_pk_bf16_f32 v84, v88, v89
	v_cvt_pk_bf16_f32 v85, v90, v91
; #define GAS __attribute__((address_space(1)))
; __device__ __forceinline__ unsigned cvt_pk_bf16(float lo, float hi) { const f32x2_t_ v = {lo, hi}; const bf16x2_t_ b = __builtin_convertvector(v, bf16x2_t_); return __builtin_bit_cast(unsigned, b); }
; __device__ __forceinline__ void gate_mul4(f32x4& v, unsigned g) { const float s = 1.0f / 255.0f; v[0] *= ub0(g) * s; v[1] *= ub1(g) * s; v[2] *= ub2(g) * s; v[3] *= ub3(g) * s; }
;     __device__ __forceinline__ void operator()(const f32x4 (&acc)[2][2][4][2], const pg8::GUnit& u, int wr, int wc, int fr, int fq) const {
;     ...
;         for (int k = 0; k < 8; ++k) { const int ai = k >> 2, m = k & 3;
; #pragma unroll
;             for (int bj = 0; bj < 2; ++bj) { f32x4 v0 = acc[ai][bj][m][0], v1 = acc[ai][bj][m][1];
;                 gate_mul4(v0, bj ? g[k].z : g[k].x); gate_mul4(v1, bj ? g[k].w : g[k].y);
;                 u32x4 w; w.x = cvt_pk_bf16(v0[0], v0[1]); w.y = cvt_pk_bf16(v0[2], v0[3]); w.z = cvt_pk_bf16(v1[0], v1[1]); w.w = cvt_pk_bf16(v1[2], v1[3]);
;                 *(GAS u32x4*)(mp0 + (size_t)(ai * 128 + m * 16) * DM + bj * 128) = w; } }
	v_cvt_pk_bf16_f32 v86, v92, v93
	v_cvt_pk_bf16_f32 v87, v94, v95
	global_store_dwordx4 v[96:97], v[84:87], off offset:256
	s_nop 1
	v_cvt_f32_ubyte1_e32 v85, v148
	v_cvt_f32_ubyte0_e32 v84, v148
	v_pk_mul_f32 v[84:85], v[84:85], s[6:7] op_sel_hi:[1,0]
	s_nop 0
	v_pk_mul_f32 v[80:81], v[80:81], v[84:85]
	v_cvt_f32_ubyte3_e32 v85, v148
	v_cvt_f32_ubyte2_e32 v84, v148
	v_pk_mul_f32 v[84:85], v[84:85], s[6:7] op_sel_hi:[1,0]
	s_nop 0
	v_pk_mul_f32 v[82:83], v[82:83], v[84:85]
	v_cvt_f32_ubyte1_e32 v85, v149
	v_cvt_f32_ubyte0_e32 v84, v149
	v_pk_mul_f32 v[84:85], v[84:85], s[6:7] op_sel_hi:[1,0]
	s_nop 0
	v_pk_mul_f32 v[84:85], v[76:77], v[84:85]
	v_cvt_f32_ubyte3_e32 v77, v149
	v_cvt_f32_ubyte2_e32 v76, v149
	v_pk_mul_f32 v[76:77], v[76:77], s[6:7] op_sel_hi:[1,0]
	s_nop 0
	v_pk_mul_f32 v[86:87], v[78:79], v[76:77]
	v_cvt_pk_bf16_f32 v76, v80, v81
	v_add_co_u32_e32 v80, vcc, s9, v2
	v_cvt_pk_bf16_f32 v77, v82, v83
	v_cvt_pk_bf16_f32 v78, v84, v85
	v_cvt_pk_bf16_f32 v79, v86, v87
	v_addc_co_u32_e32 v81, vcc, 0, v3, vcc
	global_store_dwordx4 v[80:81], v[76:79], off
	s_mov_b32 s9, s13
	s_nop 0
	v_cvt_f32_ubyte1_e32 v77, v150
	v_cvt_f32_ubyte0_e32 v76, v150
	v_pk_mul_f32 v[76:77], v[76:77], s[6:7] op_sel_hi:[1,0]
	s_nop 0
	v_pk_mul_f32 v[72:73], v[72:73], v[76:77]
	v_cvt_f32_ubyte3_e32 v77, v150
	v_cvt_f32_ubyte2_e32 v76, v150
	v_pk_mul_f32 v[76:77], v[76:77], s[6:7] op_sel_hi:[1,0]
	s_nop 0
	v_pk_mul_f32 v[74:75], v[74:75], v[76:77]
	v_cvt_f32_ubyte1_e32 v77, v151
	v_cvt_f32_ubyte0_e32 v76, v151
	v_pk_mul_f32 v[76:77], v[76:77], s[6:7] op_sel_hi:[1,0]
	s_nop 0
	v_pk_mul_f32 v[76:77], v[68:69], v[76:77]
	v_cvt_f32_ubyte3_e32 v69, v151
	v_cvt_f32_ubyte2_e32 v68, v151
	v_pk_mul_f32 v[68:69], v[68:69], s[6:7] op_sel_hi:[1,0]
	s_nop 0
	v_pk_mul_f32 v[78:79], v[70:71], v[68:69]
	v_cvt_pk_bf16_f32 v68, v72, v73
	v_cvt_pk_bf16_f32 v69, v74, v75
	v_cvt_pk_bf16_f32 v70, v76, v77
	v_cvt_pk_bf16_f32 v71, v78, v79
	global_store_dwordx4 v[80:81], v[68:71], off offset:256
	s_nop 1
	v_cvt_f32_ubyte1_e32 v69, v144
	v_cvt_f32_ubyte0_e32 v68, v144
	v_pk_mul_f32 v[68:69], v[68:69], s[6:7] op_sel_hi:[1,0]
	s_nop 0
	v_pk_mul_f32 v[64:65], v[64:65], v[68:69]
	v_cvt_f32_ubyte3_e32 v69, v144
	v_cvt_f32_ubyte2_e32 v68, v144
	v_pk_mul_f32 v[68:69], v[68:69], s[6:7] op_sel_hi:[1,0]
	s_nop 0
	v_pk_mul_f32 v[66:67], v[66:67], v[68:69]
	v_cvt_f32_ubyte1_e32 v69, v145
	v_cvt_f32_ubyte0_e32 v68, v145
	v_pk_mul_f32 v[68:69], v[68:69], s[6:7] op_sel_hi:[1,0]
	s_nop 0
	v_pk_mul_f32 v[68:69], v[60:61], v[68:69]
	v_cvt_f32_ubyte3_e32 v61, v145
	v_cvt_f32_ubyte2_e32 v60, v145
	v_pk_mul_f32 v[60:61], v[60:61], s[6:7] op_sel_hi:[1,0]
	s_nop 0
	v_pk_mul_f32 v[70:71], v[62:63], v[60:61]
	v_cvt_pk_bf16_f32 v60, v64, v65
	v_add_co_u32_e32 v64, vcc, s8, v2
	v_cvt_pk_bf16_f32 v61, v66, v67
	v_cvt_pk_bf16_f32 v62, v68, v69
	v_cvt_pk_bf16_f32 v63, v70, v71
	v_addc_co_u32_e32 v65, vcc, 0, v3, vcc
	global_store_dwordx4 v[64:65], v[60:63], off
	s_mov_b32 s8, 0x140000
	s_nop 0
	v_cvt_f32_ubyte1_e32 v61, v146
	v_cvt_f32_ubyte0_e32 v60, v146
	v_pk_mul_f32 v[60:61], v[60:61], s[6:7] op_sel_hi:[1,0]
	s_nop 0
	v_pk_mul_f32 v[56:57], v[56:57], v[60:61]
	v_cvt_f32_ubyte3_e32 v61, v146
	v_cvt_f32_ubyte2_e32 v60, v146
	v_pk_mul_f32 v[60:61], v[60:61], s[6:7] op_sel_hi:[1,0]
	s_nop 0
	v_pk_mul_f32 v[58:59], v[58:59], v[60:61]
	v_cvt_f32_ubyte1_e32 v61, v147
	v_cvt_f32_ubyte0_e32 v60, v147
	v_pk_mul_f32 v[60:61], v[60:61], s[6:7] op_sel_hi:[1,0]
	s_nop 0
	v_pk_mul_f32 v[60:61], v[52:53], v[60:61]
	v_cvt_f32_ubyte3_e32 v53, v147
	v_cvt_f32_ubyte2_e32 v52, v147
	v_pk_mul_f32 v[52:53], v[52:53], s[6:7] op_sel_hi:[1,0]
	s_nop 0
	v_pk_mul_f32 v[62:63], v[54:55], v[52:53]
	v_cvt_pk_bf16_f32 v52, v56, v57
	v_cvt_pk_bf16_f32 v53, v58, v59
	v_cvt_pk_bf16_f32 v54, v60, v61
	v_cvt_pk_bf16_f32 v55, v62, v63
	global_store_dwordx4 v[64:65], v[52:55], off offset:256
	s_nop 1
	v_cvt_f32_ubyte1_e32 v53, v140
	v_cvt_f32_ubyte0_e32 v52, v140
	v_pk_mul_f32 v[52:53], v[52:53], s[6:7] op_sel_hi:[1,0]
	s_nop 0
	v_pk_mul_f32 v[48:49], v[48:49], v[52:53]
	v_cvt_f32_ubyte3_e32 v53, v140
	v_cvt_f32_ubyte2_e32 v52, v140
	v_pk_mul_f32 v[52:53], v[52:53], s[6:7] op_sel_hi:[1,0]
	s_nop 0
	v_pk_mul_f32 v[50:51], v[50:51], v[52:53]
	v_cvt_f32_ubyte1_e32 v53, v141
	v_cvt_f32_ubyte0_e32 v52, v141
	v_pk_mul_f32 v[52:53], v[52:53], s[6:7] op_sel_hi:[1,0]
	s_nop 0
	v_pk_mul_f32 v[52:53], v[44:45], v[52:53]
	v_cvt_f32_ubyte3_e32 v45, v141
	v_cvt_f32_ubyte2_e32 v44, v141
	v_pk_mul_f32 v[44:45], v[44:45], s[6:7] op_sel_hi:[1,0]
	s_nop 0
	v_pk_mul_f32 v[54:55], v[46:47], v[44:45]
	v_cvt_pk_bf16_f32 v44, v48, v49
	v_add_co_u32_e32 v48, vcc, s10, v2
	v_cvt_pk_bf16_f32 v45, v50, v51
	v_cvt_pk_bf16_f32 v46, v52, v53
	v_cvt_pk_bf16_f32 v47, v54, v55
; #define GAS __attribute__((address_space(1)))
; __device__ __forceinline__ unsigned cvt_pk_bf16(float lo, float hi) { const f32x2_t_ v = {lo, hi}; const bf16x2_t_ b = __builtin_convertvector(v, bf16x2_t_); return __builtin_bit_cast(unsigned, b); }
; __device__ __forceinline__ void gate_mul4(f32x4& v, unsigned g) { const float s = 1.0f / 255.0f; v[0] *= ub0(g) * s; v[1] *= ub1(g) * s; v[2] *= ub2(g) * s; v[3] *= ub3(g) * s; }
;     __device__ __forceinline__ void operator()(const f32x4 (&acc)[2][2][4][2], const pg8::GUnit& u, int wr, int wc, int fr, int fq) const {
;     ...
;         for (int k = 0; k < 8; ++k) { const int ai = k >> 2, m = k & 3;
; #pragma unroll
;             for (int bj = 0; bj < 2; ++bj) { f32x4 v0 = acc[ai][bj][m][0], v1 = acc[ai][bj][m][1];
;                 gate_mul4(v0, bj ? g[k].z : g[k].x); gate_mul4(v1, bj ? g[k].w : g[k].y);
;                 u32x4 w; w.x = cvt_pk_bf16(v0[0], v0[1]); w.y = cvt_pk_bf16(v0[2], v0[3]); w.z = cvt_pk_bf16(v1[0], v1[1]); w.w = cvt_pk_bf16(v1[2], v1[3]);
;                 *(GAS u32x4*)(mp0 + (size_t)(ai * 128 + m * 16) * DM + bj * 128) = w; } }
	v_addc_co_u32_e32 v49, vcc, 0, v3, vcc
	global_store_dwordx4 v[48:49], v[44:47], off
	s_mov_b32 s10, s12
	s_nop 0
	v_cvt_f32_ubyte1_e32 v45, v142
	v_cvt_f32_ubyte0_e32 v44, v142
	v_pk_mul_f32 v[44:45], v[44:45], s[6:7] op_sel_hi:[1,0]
	s_nop 0
	v_pk_mul_f32 v[40:41], v[40:41], v[44:45]
	v_cvt_f32_ubyte3_e32 v45, v142
	v_cvt_f32_ubyte2_e32 v44, v142
	v_pk_mul_f32 v[44:45], v[44:45], s[6:7] op_sel_hi:[1,0]
	s_nop 0
	v_pk_mul_f32 v[42:43], v[42:43], v[44:45]
	v_cvt_f32_ubyte1_e32 v45, v143
	v_cvt_f32_ubyte0_e32 v44, v143
	v_pk_mul_f32 v[44:45], v[44:45], s[6:7] op_sel_hi:[1,0]
	s_nop 0
	v_pk_mul_f32 v[44:45], v[36:37], v[44:45]
	v_cvt_f32_ubyte3_e32 v37, v143
	v_cvt_f32_ubyte2_e32 v36, v143
	v_pk_mul_f32 v[36:37], v[36:37], s[6:7] op_sel_hi:[1,0]
	s_nop 0
	v_pk_mul_f32 v[46:47], v[38:39], v[36:37]
	v_cvt_pk_bf16_f32 v36, v40, v41
	v_cvt_pk_bf16_f32 v37, v42, v43
	v_cvt_pk_bf16_f32 v38, v44, v45
	v_cvt_pk_bf16_f32 v39, v46, v47
	global_store_dwordx4 v[48:49], v[36:39], off offset:256
	s_nop 1
	v_cvt_f32_ubyte1_e32 v37, v132
	v_cvt_f32_ubyte0_e32 v36, v132
	v_pk_mul_f32 v[36:37], v[36:37], s[6:7] op_sel_hi:[1,0]
	s_nop 0
	v_pk_mul_f32 v[32:33], v[32:33], v[36:37]
	v_cvt_f32_ubyte3_e32 v37, v132
	v_cvt_f32_ubyte2_e32 v36, v132
	v_pk_mul_f32 v[36:37], v[36:37], s[6:7] op_sel_hi:[1,0]
	s_nop 0
	v_pk_mul_f32 v[34:35], v[34:35], v[36:37]
	v_cvt_f32_ubyte1_e32 v37, v133
	v_cvt_f32_ubyte0_e32 v36, v133
	v_pk_mul_f32 v[36:37], v[36:37], s[6:7] op_sel_hi:[1,0]
	s_nop 0
	v_pk_mul_f32 v[36:37], v[28:29], v[36:37]
	v_cvt_f32_ubyte3_e32 v29, v133
	v_cvt_f32_ubyte2_e32 v28, v133
	v_pk_mul_f32 v[28:29], v[28:29], s[6:7] op_sel_hi:[1,0]
	s_nop 0
	v_pk_mul_f32 v[38:39], v[30:31], v[28:29]
	v_cvt_pk_bf16_f32 v28, v32, v33
	v_add_co_u32_e32 v32, vcc, s8, v2
	v_cvt_pk_bf16_f32 v29, v34, v35
	v_cvt_pk_bf16_f32 v30, v36, v37
	v_cvt_pk_bf16_f32 v31, v38, v39
	v_addc_co_u32_e32 v33, vcc, 0, v3, vcc
	global_store_dwordx4 v[32:33], v[28:31], off
	s_mov_b32 s8, 0x160000
	s_nop 0
	v_cvt_f32_ubyte1_e32 v29, v134
	v_cvt_f32_ubyte0_e32 v28, v134
	v_pk_mul_f32 v[28:29], v[28:29], s[6:7] op_sel_hi:[1,0]
	s_nop 0
	v_pk_mul_f32 v[24:25], v[24:25], v[28:29]
	v_cvt_f32_ubyte3_e32 v29, v134
	v_cvt_f32_ubyte2_e32 v28, v134
	v_pk_mul_f32 v[28:29], v[28:29], s[6:7] op_sel_hi:[1,0]
	s_nop 0
	v_pk_mul_f32 v[26:27], v[26:27], v[28:29]
	v_cvt_f32_ubyte1_e32 v29, v135
	v_cvt_f32_ubyte0_e32 v28, v135
	v_pk_mul_f32 v[28:29], v[28:29], s[6:7] op_sel_hi:[1,0]
	s_nop 0
	v_pk_mul_f32 v[28:29], v[20:21], v[28:29]
	v_cvt_f32_ubyte3_e32 v21, v135
	v_cvt_f32_ubyte2_e32 v20, v135
	v_pk_mul_f32 v[20:21], v[20:21], s[6:7] op_sel_hi:[1,0]
	s_nop 0
	v_pk_mul_f32 v[30:31], v[22:23], v[20:21]
	v_cvt_pk_bf16_f32 v20, v24, v25
	v_cvt_pk_bf16_f32 v21, v26, v27
	v_cvt_pk_bf16_f32 v22, v28, v29
	v_cvt_pk_bf16_f32 v23, v30, v31
	global_store_dwordx4 v[32:33], v[20:23], off offset:256
	s_nop 1
	v_cvt_f32_ubyte1_e32 v21, v136
	v_cvt_f32_ubyte0_e32 v20, v136
	v_pk_mul_f32 v[20:21], v[20:21], s[6:7] op_sel_hi:[1,0]
	s_nop 0
	v_pk_mul_f32 v[16:17], v[16:17], v[20:21]
	v_cvt_f32_ubyte3_e32 v21, v136
	v_cvt_f32_ubyte2_e32 v20, v136
	v_pk_mul_f32 v[20:21], v[20:21], s[6:7] op_sel_hi:[1,0]
	s_nop 0
	v_pk_mul_f32 v[18:19], v[18:19], v[20:21]
	v_cvt_f32_ubyte1_e32 v21, v137
	v_cvt_f32_ubyte0_e32 v20, v137
	v_pk_mul_f32 v[20:21], v[20:21], s[6:7] op_sel_hi:[1,0]
	s_nop 0
	v_pk_mul_f32 v[20:21], v[12:13], v[20:21]
	v_cvt_f32_ubyte3_e32 v13, v137
	v_cvt_f32_ubyte2_e32 v12, v137
	v_pk_mul_f32 v[12:13], v[12:13], s[6:7] op_sel_hi:[1,0]
	s_nop 0
	v_pk_mul_f32 v[22:23], v[14:15], v[12:13]
	v_cvt_pk_bf16_f32 v12, v16, v17
	v_add_co_u32_e32 v16, vcc, s8, v2
	v_cvt_f32_ubyte2_e32 v2, v138
	s_nop 0
	v_addc_co_u32_e32 v17, vcc, 0, v3, vcc
	v_cvt_f32_ubyte3_e32 v3, v138
	v_pk_mul_f32 v[2:3], v[2:3], s[6:7] op_sel_hi:[1,0]
	v_cvt_pk_bf16_f32 v13, v18, v19
	v_pk_mul_f32 v[10:11], v[10:11], v[2:3]
	v_cvt_f32_ubyte1_e32 v3, v138
	v_cvt_f32_ubyte0_e32 v2, v138
	v_pk_mul_f32 v[2:3], v[2:3], s[6:7] op_sel_hi:[1,0]
	v_cvt_pk_bf16_f32 v14, v20, v21
	v_pk_mul_f32 v[2:3], v[8:9], v[2:3]
	v_cvt_f32_ubyte1_e32 v9, v139
	v_cvt_f32_ubyte0_e32 v8, v139
	v_pk_mul_f32 v[8:9], v[8:9], s[6:7] op_sel_hi:[1,0]
	v_cvt_pk_bf16_f32 v15, v22, v23
	v_pk_mul_f32 v[4:5], v[4:5], v[8:9]
	v_cvt_f32_ubyte3_e32 v9, v139
	v_cvt_f32_ubyte2_e32 v8, v139
	v_pk_mul_f32 v[8:9], v[8:9], s[6:7] op_sel_hi:[1,0]
	v_cvt_pk_bf16_f32 v2, v2, v3
	v_pk_mul_f32 v[6:7], v[6:7], v[8:9]
	v_cvt_pk_bf16_f32 v3, v10, v11
	v_cvt_pk_bf16_f32 v4, v4, v5
	v_cvt_pk_bf16_f32 v5, v6, v7
	s_and_b64 vcc, exec, s[4:5]
	s_mov_b32 s8, s47
	global_store_dwordx4 v[16:17], v[12:15], off
	global_store_dwordx4 v[16:17], v[2:5], off offset:256
	s_cbranch_vccnz .LBB0_788

; #define GAS __attribute__((address_space(1)))
;     __device__ __forceinline__ void mid(f32x4 (&acc)[2][2][4][2], const pg8::GUnit& u, int b, int wr, int wc, int fr, int fq) const {
;     ...
;         const GAS unsigned char* gp = (const GAS unsigned char*)P + (size_t)(u.pm * 256 + (wr * 4 + wc) * 32 + fq) * (INW * 2) + (GA * 2 + (b * 16 + u.pn) * 256 + fr * 16);
;         u32x4 gn[8], gd[8];
; #pragma unroll
;         for (int k = 0; k < 8; ++k) { const GAS unsigned char* q = gp + (size_t)(k * 4) * (INW * 2); gn[k] = *(const GAS u32x4*)q; gd[k] = *(const GAS u32x4*)(q + DM); }
; #pragma unroll
;         for (int k = 0; k < 8; ++k) { const int ai = k >> 2, m = k & 3;
;             gate_ratio4(acc[ai][0][m][0], gn[k].x, gd[k].x); gate_ratio4(acc[ai][0][m][1], gn[k].y, gd[k].y); gate_ratio4(acc[ai][1][m][0], gn[k].z, gd[k].z); gate_ratio4(acc[ai][1][m][1], gn[k].w, gd[k].w); }
.LBB0_783:
	s_andn2_b64 vcc, exec, s[8:9]
	s_cbranch_vccnz .LBB0_785
	v_mbcnt_lo_u32_b32 v0, -1, 0
	v_mbcnt_hi_u32_b32 v0, -1, v0
	s_cmpk_lg_i32 s89, 0xc00
	s_cbranch_scc1 .Lbr_mid1_load
	s_cmpk_eq_i32 s89, 0xc00
	v_ashrrev_i32_e32 v2, 4, v0
	v_add_u32_e32 v2, s84, v2
	v_mad_i64_i32 v[2:3], s[8:9], v2, s93, v[200:201]
	s_cselect_b32 s8, 0, 0x1000
	v_lshlrev_b32_e32 v0, 4, v0
	s_add_i32 s8, s87, s8
	v_and_b32_e32 v0, 0xf0, v0
	v_or_b32_e32 v132, s8, v0
	v_ashrrev_i32_e32 v133, 31, v132
	v_lshl_add_u64 v[2:3], v[2:3], 0, v[132:133]
	v_add_co_u32_e32 v132, vcc, s35, v2
	global_load_dwordx4 v[188:191], v[2:3], off
	s_nop 0
	v_addc_co_u32_e32 v133, vcc, 0, v3, vcc
	global_load_dwordx4 v[192:195], v[132:133], off
	s_mov_b32 s8, 0x31000
	v_add_co_u32_e32 v132, vcc, s8, v2
	s_mov_b32 s8, 0x61000
	s_nop 0
	v_addc_co_u32_e32 v133, vcc, 0, v3, vcc
	global_load_dwordx4 v[180:183], v[132:133], off offset:-4096
	global_load_dwordx4 v[184:187], v[132:133], off
	v_add_co_u32_e32 v132, vcc, s8, v2
	s_mov_b32 s8, 0x91000
	s_nop 0
	v_addc_co_u32_e32 v133, vcc, 0, v3, vcc
	global_load_dwordx4 v[172:175], v[132:133], off offset:-4096
	global_load_dwordx4 v[176:179], v[132:133], off
	v_add_co_u32_e32 v132, vcc, s8, v2
	s_mov_b32 s8, 0xc1000
	s_nop 0
	v_addc_co_u32_e32 v133, vcc, 0, v3, vcc
	global_load_dwordx4 v[164:167], v[132:133], off offset:-4096
	global_load_dwordx4 v[168:171], v[132:133], off
	v_add_co_u32_e32 v132, vcc, s8, v2
	s_mov_b32 s8, 0xf1000
	s_nop 0
	v_addc_co_u32_e32 v133, vcc, 0, v3, vcc
	global_load_dwordx4 v[156:159], v[132:133], off offset:-4096
	global_load_dwordx4 v[160:163], v[132:133], off
	v_add_co_u32_e32 v132, vcc, s8, v2
	s_mov_b32 s8, 0x121000
	s_nop 0
	v_addc_co_u32_e32 v133, vcc, 0, v3, vcc
	global_load_dwordx4 v[148:151], v[132:133], off offset:-4096
	global_load_dwordx4 v[152:155], v[132:133], off
	v_add_co_u32_e32 v132, vcc, s8, v2
	s_mov_b32 s8, 0x151000
	s_nop 0
	v_addc_co_u32_e32 v133, vcc, 0, v3, vcc
	v_add_co_u32_e32 v2, vcc, s8, v2
	global_load_dwordx4 v[140:143], v[132:133], off offset:-4096
	global_load_dwordx4 v[144:147], v[132:133], off
	v_addc_co_u32_e32 v3, vcc, 0, v3, vcc
	global_load_dwordx4 v[132:135], v[2:3], off offset:-4096
	global_load_dwordx4 v[136:139], v[2:3], off
.Lbr_mid_wait:
	s_waitcnt vmcnt(0)
	v_mov_b32_e32 v215, v192
	v_mov_b32_e32 v216, v193
	v_mov_b32_e32 v217, v194
	v_mov_b32_e32 v218, v195
	v_mov_b32_e32 v219, v184
	v_mov_b32_e32 v220, v185
	v_mov_b32_e32 v221, v186
	v_mov_b32_e32 v222, v187
	v_mov_b32_e32 v223, v176
	v_mov_b32_e32 v224, v177
	v_mov_b32_e32 v225, v178
	v_mov_b32_e32 v226, v179
	v_mov_b32_e32 v227, v168
	v_mov_b32_e32 v228, v169
	v_mov_b32_e32 v229, v170
	v_mov_b32_e32 v230, v171
	v_mov_b32_e32 v231, v160
	v_mov_b32_e32 v232, v161
	v_mov_b32_e32 v233, v162
	v_mov_b32_e32 v234, v163
	v_mov_b32_e32 v235, v152
	v_mov_b32_e32 v236, v153
	v_mov_b32_e32 v237, v154
	v_mov_b32_e32 v238, v155
	v_mov_b32_e32 v239, v144
	v_mov_b32_e32 v240, v145
	v_mov_b32_e32 v241, v146
	v_mov_b32_e32 v242, v147
	v_mov_b32_e32 v243, v136
	v_mov_b32_e32 v245, v137
	v_mov_b32_e32 v246, v138
	v_mov_b32_e32 v247, v139
	v_cvt_f32_ubyte1_e32 v213, v188
	v_cvt_f32_ubyte0_e32 v212, v188
	v_cvt_f32_ubyte3_e32 v211, v188
	v_cvt_f32_ubyte0_e32 v0, v192
	v_rcp_iflag_f32_e32 v2, v0
	v_cvt_f32_ubyte1_e32 v0, v192
	v_rcp_iflag_f32_e32 v3, v0
	v_cvt_f32_ubyte2_e32 v0, v192
	v_rcp_iflag_f32_e32 v208, v0
	v_cvt_f32_ubyte3_e32 v0, v192
	v_rcp_iflag_f32_e32 v209, v0
	v_pk_mul_f32 v[2:3], v[2:3], v[212:213]
	v_cvt_f32_ubyte0_e32 v0, v193
	v_pk_mul_f32 v[128:129], v[128:129], v[2:3]
	v_rcp_iflag_f32_e32 v2, v0
	v_cvt_f32_ubyte1_e32 v0, v193
	v_rcp_iflag_f32_e32 v3, v0
	v_cvt_f32_ubyte2_e32 v210, v188
	v_cvt_f32_ubyte2_e32 v0, v193
	v_pk_mul_f32 v[208:209], v[208:209], v[210:211]
	v_rcp_iflag_f32_e32 v192, v0
	v_cvt_f32_ubyte3_e32 v0, v193
	v_cvt_f32_ubyte1_e32 v211, v189
	v_cvt_f32_ubyte0_e32 v210, v189
	v_rcp_iflag_f32_e32 v193, v0
	v_pk_mul_f32 v[2:3], v[2:3], v[210:211]
	v_cvt_f32_ubyte0_e32 v0, v194
	v_pk_mul_f32 v[124:125], v[124:125], v[2:3]
	v_rcp_iflag_f32_e32 v2, v0
	v_cvt_f32_ubyte1_e32 v0, v194
	v_rcp_iflag_f32_e32 v3, v0
	v_pk_mul_f32 v[130:131], v[130:131], v[208:209]
	v_cvt_f32_ubyte3_e32 v209, v189
	v_cvt_f32_ubyte2_e32 v208, v189
	v_pk_mul_f32 v[188:189], v[192:193], v[208:209]
	v_cvt_f32_ubyte2_e32 v0, v194
	v_pk_mul_f32 v[126:127], v[126:127], v[188:189]
	v_rcp_iflag_f32_e32 v188, v0
	v_cvt_f32_ubyte3_e32 v0, v194
	v_cvt_f32_ubyte1_e32 v209, v190
	v_cvt_f32_ubyte0_e32 v208, v190
	v_rcp_iflag_f32_e32 v189, v0
	v_pk_mul_f32 v[2:3], v[2:3], v[208:209]
	v_cvt_f32_ubyte0_e32 v0, v195
	v_pk_mul_f32 v[120:121], v[120:121], v[2:3]
	v_rcp_iflag_f32_e32 v2, v0
	v_cvt_f32_ubyte1_e32 v0, v195
	v_rcp_iflag_f32_e32 v3, v0
	v_cvt_f32_ubyte3_e32 v193, v190
	v_cvt_f32_ubyte2_e32 v192, v190
	v_pk_mul_f32 v[188:189], v[188:189], v[192:193]
	v_cvt_f32_ubyte2_e32 v0, v195
	v_pk_mul_f32 v[122:123], v[122:123], v[188:189]
	v_rcp_iflag_f32_e32 v188, v0
	v_cvt_f32_ubyte3_e32 v0, v195
	v_cvt_f32_ubyte1_e32 v195, v191
	v_cvt_f32_ubyte0_e32 v194, v191
	v_rcp_iflag_f32_e32 v189, v0
	v_pk_mul_f32 v[2:3], v[2:3], v[194:195]
	v_cvt_f32_ubyte0_e32 v0, v184
	v_pk_mul_f32 v[116:117], v[116:117], v[2:3]
	v_rcp_iflag_f32_e32 v2, v0
	v_cvt_f32_ubyte1_e32 v0, v184
	v_rcp_iflag_f32_e32 v3, v0
	v_cvt_f32_ubyte3_e32 v193, v191
	v_cvt_f32_ubyte2_e32 v192, v191
	v_pk_mul_f32 v[188:189], v[188:189], v[192:193]
	v_cvt_f32_ubyte2_e32 v0, v184
	v_pk_mul_f32 v[118:119], v[118:119], v[188:189]
	v_rcp_iflag_f32_e32 v188, v0
	v_cvt_f32_ubyte3_e32 v0, v184
	v_cvt_f32_ubyte1_e32 v193, v180
	v_cvt_f32_ubyte0_e32 v192, v180
	v_rcp_iflag_f32_e32 v189, v0
; __device__ __forceinline__ float ub0(unsigned w) { return (float)(w & 0xffu); }
; __device__ __forceinline__ float ub1(unsigned w) { return (float)((w >> 8) & 0xffu); }
; __device__ __forceinline__ float ub2(unsigned w) { return (float)((w >> 16) & 0xffu); }
; __device__ __forceinline__ float ub3(unsigned w) { return (float)(w >> 24); }
; __device__ __forceinline__ void gate_ratio4(f32x4& v, unsigned n, unsigned d) {
;     v[0] *= ub0(n) * __builtin_amdgcn_rcpf(ub0(d)); v[1] *= ub1(n) * __builtin_amdgcn_rcpf(ub1(d)); v[2] *= ub2(n) * __builtin_amdgcn_rcpf(ub2(d)); v[3] *= ub3(n) * __builtin_amdgcn_rcpf(ub3(d)); }
;     __device__ __forceinline__ void mid(f32x4 (&acc)[2][2][4][2], const pg8::GUnit& u, int b, int wr, int wc, int fr, int fq) const {
;     ...
;         for (int k = 0; k < 8; ++k) { const int ai = k >> 2, m = k & 3;
;             gate_ratio4(acc[ai][0][m][0], gn[k].x, gd[k].x); gate_ratio4(acc[ai][0][m][1], gn[k].y, gd[k].y); gate_ratio4(acc[ai][1][m][0], gn[k].z, gd[k].z); gate_ratio4(acc[ai][1][m][1], gn[k].w, gd[k].w); }
	v_pk_mul_f32 v[2:3], v[2:3], v[192:193]
	v_cvt_f32_ubyte0_e32 v0, v185
	v_pk_mul_f32 v[112:113], v[112:113], v[2:3]
	v_rcp_iflag_f32_e32 v2, v0
	v_cvt_f32_ubyte1_e32 v0, v185
	v_rcp_iflag_f32_e32 v3, v0
	v_cvt_f32_ubyte3_e32 v191, v180
	v_cvt_f32_ubyte2_e32 v190, v180
	v_cvt_f32_ubyte2_e32 v0, v185
	v_pk_mul_f32 v[188:189], v[188:189], v[190:191]
	v_rcp_iflag_f32_e32 v184, v0
	v_cvt_f32_ubyte3_e32 v0, v185
	v_cvt_f32_ubyte1_e32 v191, v181
	v_cvt_f32_ubyte0_e32 v190, v181
	v_rcp_iflag_f32_e32 v185, v0
	v_pk_mul_f32 v[2:3], v[2:3], v[190:191]
	v_cvt_f32_ubyte0_e32 v0, v186
	v_pk_mul_f32 v[108:109], v[108:109], v[2:3]
	v_rcp_iflag_f32_e32 v2, v0
	v_cvt_f32_ubyte1_e32 v0, v186
	v_rcp_iflag_f32_e32 v3, v0
	v_pk_mul_f32 v[114:115], v[114:115], v[188:189]
	v_cvt_f32_ubyte3_e32 v189, v181
	v_cvt_f32_ubyte2_e32 v188, v181
	v_pk_mul_f32 v[180:181], v[184:185], v[188:189]
	v_cvt_f32_ubyte2_e32 v0, v186
	v_pk_mul_f32 v[110:111], v[110:111], v[180:181]
	v_rcp_iflag_f32_e32 v180, v0
	v_cvt_f32_ubyte3_e32 v0, v186
	v_cvt_f32_ubyte1_e32 v189, v182
	v_cvt_f32_ubyte0_e32 v188, v182
	v_rcp_iflag_f32_e32 v181, v0
	v_pk_mul_f32 v[2:3], v[2:3], v[188:189]
	v_cvt_f32_ubyte0_e32 v0, v187
	v_pk_mul_f32 v[104:105], v[104:105], v[2:3]
	v_rcp_iflag_f32_e32 v2, v0
	v_cvt_f32_ubyte1_e32 v0, v187
	v_rcp_iflag_f32_e32 v3, v0
	v_cvt_f32_ubyte3_e32 v185, v182
	v_cvt_f32_ubyte2_e32 v184, v182
	v_pk_mul_f32 v[180:181], v[180:181], v[184:185]
	v_cvt_f32_ubyte2_e32 v0, v187
	v_pk_mul_f32 v[106:107], v[106:107], v[180:181]
	v_rcp_iflag_f32_e32 v180, v0
	v_cvt_f32_ubyte3_e32 v0, v187
	v_cvt_f32_ubyte1_e32 v187, v183
	v_cvt_f32_ubyte0_e32 v186, v183
	v_rcp_iflag_f32_e32 v181, v0
	v_pk_mul_f32 v[2:3], v[2:3], v[186:187]
	v_cvt_f32_ubyte0_e32 v0, v176
	v_pk_mul_f32 v[100:101], v[100:101], v[2:3]
	v_rcp_iflag_f32_e32 v2, v0
	v_cvt_f32_ubyte1_e32 v0, v176
	v_rcp_iflag_f32_e32 v3, v0
	v_cvt_f32_ubyte3_e32 v185, v183
	v_cvt_f32_ubyte2_e32 v184, v183
	v_pk_mul_f32 v[180:181], v[180:181], v[184:185]
	v_cvt_f32_ubyte2_e32 v0, v176
	v_pk_mul_f32 v[102:103], v[102:103], v[180:181]
	v_rcp_iflag_f32_e32 v180, v0
	v_cvt_f32_ubyte3_e32 v0, v176
	v_cvt_f32_ubyte1_e32 v185, v172
	v_cvt_f32_ubyte0_e32 v184, v172
	v_rcp_iflag_f32_e32 v181, v0
	v_pk_mul_f32 v[2:3], v[2:3], v[184:185]
	v_cvt_f32_ubyte0_e32 v0, v177
	v_pk_mul_f32 v[96:97], v[96:97], v[2:3]
	v_rcp_iflag_f32_e32 v2, v0
	v_cvt_f32_ubyte1_e32 v0, v177
	v_rcp_iflag_f32_e32 v3, v0
	v_cvt_f32_ubyte3_e32 v183, v172
	v_cvt_f32_ubyte2_e32 v182, v172
	v_cvt_f32_ubyte2_e32 v0, v177
	v_pk_mul_f32 v[180:181], v[180:181], v[182:183]
	v_rcp_iflag_f32_e32 v176, v0
	v_cvt_f32_ubyte3_e32 v0, v177
	v_cvt_f32_ubyte1_e32 v183, v173
	v_cvt_f32_ubyte0_e32 v182, v173
	v_rcp_iflag_f32_e32 v177, v0
	v_pk_mul_f32 v[2:3], v[2:3], v[182:183]
	v_cvt_f32_ubyte0_e32 v0, v178
	v_pk_mul_f32 v[92:93], v[92:93], v[2:3]
	v_rcp_iflag_f32_e32 v2, v0
	v_cvt_f32_ubyte1_e32 v0, v178
	v_rcp_iflag_f32_e32 v3, v0
	v_pk_mul_f32 v[98:99], v[98:99], v[180:181]
	v_cvt_f32_ubyte3_e32 v181, v173
	v_cvt_f32_ubyte2_e32 v180, v173
	v_pk_mul_f32 v[172:173], v[176:177], v[180:181]
	v_cvt_f32_ubyte2_e32 v0, v178
	v_pk_mul_f32 v[94:95], v[94:95], v[172:173]
	v_rcp_iflag_f32_e32 v172, v0
	v_cvt_f32_ubyte3_e32 v0, v178
	v_cvt_f32_ubyte1_e32 v181, v174
	v_cvt_f32_ubyte0_e32 v180, v174
	v_rcp_iflag_f32_e32 v173, v0
	v_pk_mul_f32 v[2:3], v[2:3], v[180:181]
	v_cvt_f32_ubyte0_e32 v0, v179
	v_pk_mul_f32 v[88:89], v[88:89], v[2:3]
	v_rcp_iflag_f32_e32 v2, v0
	v_cvt_f32_ubyte1_e32 v0, v179
	v_rcp_iflag_f32_e32 v3, v0
	v_cvt_f32_ubyte3_e32 v177, v174
	v_cvt_f32_ubyte2_e32 v176, v174
	v_pk_mul_f32 v[172:173], v[172:173], v[176:177]
	v_cvt_f32_ubyte2_e32 v0, v179
	v_pk_mul_f32 v[90:91], v[90:91], v[172:173]
	v_rcp_iflag_f32_e32 v172, v0
	v_cvt_f32_ubyte3_e32 v0, v179
	v_cvt_f32_ubyte1_e32 v179, v175
	v_cvt_f32_ubyte0_e32 v178, v175
	v_rcp_iflag_f32_e32 v173, v0
	v_pk_mul_f32 v[2:3], v[2:3], v[178:179]
	v_cvt_f32_ubyte0_e32 v0, v168
	v_pk_mul_f32 v[84:85], v[84:85], v[2:3]
	v_rcp_iflag_f32_e32 v2, v0
	v_cvt_f32_ubyte1_e32 v0, v168
	v_rcp_iflag_f32_e32 v3, v0
	v_cvt_f32_ubyte3_e32 v177, v175
	v_cvt_f32_ubyte2_e32 v176, v175
	v_pk_mul_f32 v[172:173], v[172:173], v[176:177]
	v_cvt_f32_ubyte2_e32 v0, v168
	v_pk_mul_f32 v[86:87], v[86:87], v[172:173]
	v_rcp_iflag_f32_e32 v172, v0
	v_cvt_f32_ubyte3_e32 v0, v168
	v_cvt_f32_ubyte1_e32 v177, v164
	v_cvt_f32_ubyte0_e32 v176, v164
	v_rcp_iflag_f32_e32 v173, v0
	v_pk_mul_f32 v[2:3], v[2:3], v[176:177]
	v_cvt_f32_ubyte0_e32 v0, v169
	v_pk_mul_f32 v[80:81], v[80:81], v[2:3]
	v_rcp_iflag_f32_e32 v2, v0
	v_cvt_f32_ubyte1_e32 v0, v169
	v_rcp_iflag_f32_e32 v3, v0
	v_cvt_f32_ubyte3_e32 v175, v164
	v_cvt_f32_ubyte2_e32 v174, v164
	v_cvt_f32_ubyte2_e32 v0, v169
	v_pk_mul_f32 v[172:173], v[172:173], v[174:175]
	v_rcp_iflag_f32_e32 v168, v0
	v_cvt_f32_ubyte3_e32 v0, v169
	v_cvt_f32_ubyte1_e32 v175, v165
	v_cvt_f32_ubyte0_e32 v174, v165
	v_rcp_iflag_f32_e32 v169, v0
	v_pk_mul_f32 v[2:3], v[2:3], v[174:175]
	v_cvt_f32_ubyte0_e32 v0, v170
	v_pk_mul_f32 v[76:77], v[76:77], v[2:3]
	v_rcp_iflag_f32_e32 v2, v0
	v_cvt_f32_ubyte1_e32 v0, v170
	v_rcp_iflag_f32_e32 v3, v0
	v_pk_mul_f32 v[82:83], v[82:83], v[172:173]
	v_cvt_f32_ubyte3_e32 v173, v165
	v_cvt_f32_ubyte2_e32 v172, v165
	v_pk_mul_f32 v[164:165], v[168:169], v[172:173]
	v_cvt_f32_ubyte2_e32 v0, v170
	v_pk_mul_f32 v[78:79], v[78:79], v[164:165]
	v_rcp_iflag_f32_e32 v164, v0
	v_cvt_f32_ubyte3_e32 v0, v170
	v_cvt_f32_ubyte1_e32 v173, v166
	v_cvt_f32_ubyte0_e32 v172, v166
	v_rcp_iflag_f32_e32 v165, v0
	v_pk_mul_f32 v[2:3], v[2:3], v[172:173]
	v_cvt_f32_ubyte0_e32 v0, v171
	v_pk_mul_f32 v[72:73], v[72:73], v[2:3]
	v_rcp_iflag_f32_e32 v2, v0
; __device__ __forceinline__ float ub0(unsigned w) { return (float)(w & 0xffu); }
; __device__ __forceinline__ float ub1(unsigned w) { return (float)((w >> 8) & 0xffu); }
; __device__ __forceinline__ float ub2(unsigned w) { return (float)((w >> 16) & 0xffu); }
; __device__ __forceinline__ float ub3(unsigned w) { return (float)(w >> 24); }
; __device__ __forceinline__ void gate_ratio4(f32x4& v, unsigned n, unsigned d) {
;     v[0] *= ub0(n) * __builtin_amdgcn_rcpf(ub0(d)); v[1] *= ub1(n) * __builtin_amdgcn_rcpf(ub1(d)); v[2] *= ub2(n) * __builtin_amdgcn_rcpf(ub2(d)); v[3] *= ub3(n) * __builtin_amdgcn_rcpf(ub3(d)); }
;     __device__ __forceinline__ void mid(f32x4 (&acc)[2][2][4][2], const pg8::GUnit& u, int b, int wr, int wc, int fr, int fq) const {
;     ...
;         for (int k = 0; k < 8; ++k) { const int ai = k >> 2, m = k & 3;
;             gate_ratio4(acc[ai][0][m][0], gn[k].x, gd[k].x); gate_ratio4(acc[ai][0][m][1], gn[k].y, gd[k].y); gate_ratio4(acc[ai][1][m][0], gn[k].z, gd[k].z); gate_ratio4(acc[ai][1][m][1], gn[k].w, gd[k].w); }
	v_cvt_f32_ubyte1_e32 v0, v171
	v_rcp_iflag_f32_e32 v3, v0
	v_cvt_f32_ubyte3_e32 v169, v166
	v_cvt_f32_ubyte2_e32 v168, v166
	v_pk_mul_f32 v[164:165], v[164:165], v[168:169]
	v_cvt_f32_ubyte2_e32 v0, v171
	v_pk_mul_f32 v[74:75], v[74:75], v[164:165]
	v_rcp_iflag_f32_e32 v164, v0
	v_cvt_f32_ubyte3_e32 v0, v171
	v_cvt_f32_ubyte1_e32 v171, v167
	v_cvt_f32_ubyte0_e32 v170, v167
	v_rcp_iflag_f32_e32 v165, v0
	v_pk_mul_f32 v[2:3], v[2:3], v[170:171]
	v_cvt_f32_ubyte0_e32 v0, v160
	v_pk_mul_f32 v[68:69], v[68:69], v[2:3]
	v_rcp_iflag_f32_e32 v2, v0
	v_cvt_f32_ubyte1_e32 v0, v160
	v_rcp_iflag_f32_e32 v3, v0
	v_cvt_f32_ubyte3_e32 v169, v167
	v_cvt_f32_ubyte2_e32 v168, v167
	v_pk_mul_f32 v[164:165], v[164:165], v[168:169]
	v_cvt_f32_ubyte2_e32 v0, v160
	v_pk_mul_f32 v[70:71], v[70:71], v[164:165]
	v_rcp_iflag_f32_e32 v164, v0
	v_cvt_f32_ubyte3_e32 v0, v160
	v_cvt_f32_ubyte1_e32 v169, v156
	v_cvt_f32_ubyte0_e32 v168, v156
	v_rcp_iflag_f32_e32 v165, v0
	v_pk_mul_f32 v[2:3], v[2:3], v[168:169]
	v_cvt_f32_ubyte0_e32 v0, v161
	v_pk_mul_f32 v[64:65], v[64:65], v[2:3]
	v_rcp_iflag_f32_e32 v2, v0
	v_cvt_f32_ubyte1_e32 v0, v161
	v_rcp_iflag_f32_e32 v3, v0
	v_cvt_f32_ubyte3_e32 v167, v156
	v_cvt_f32_ubyte2_e32 v166, v156
	v_cvt_f32_ubyte2_e32 v0, v161
	v_pk_mul_f32 v[164:165], v[164:165], v[166:167]
	v_rcp_iflag_f32_e32 v160, v0
	v_cvt_f32_ubyte3_e32 v0, v161
	v_cvt_f32_ubyte1_e32 v167, v157
	v_cvt_f32_ubyte0_e32 v166, v157
	v_rcp_iflag_f32_e32 v161, v0
	v_pk_mul_f32 v[2:3], v[2:3], v[166:167]
	v_cvt_f32_ubyte0_e32 v0, v162
	v_pk_mul_f32 v[60:61], v[60:61], v[2:3]
	v_rcp_iflag_f32_e32 v2, v0
	v_cvt_f32_ubyte1_e32 v0, v162
	v_rcp_iflag_f32_e32 v3, v0
	v_pk_mul_f32 v[66:67], v[66:67], v[164:165]
	v_cvt_f32_ubyte3_e32 v165, v157
	v_cvt_f32_ubyte2_e32 v164, v157
	v_pk_mul_f32 v[156:157], v[160:161], v[164:165]
	v_cvt_f32_ubyte2_e32 v0, v162
	v_pk_mul_f32 v[62:63], v[62:63], v[156:157]
	v_rcp_iflag_f32_e32 v156, v0
	v_cvt_f32_ubyte3_e32 v0, v162
	v_cvt_f32_ubyte1_e32 v165, v158
	v_cvt_f32_ubyte0_e32 v164, v158
	v_rcp_iflag_f32_e32 v157, v0
	v_pk_mul_f32 v[2:3], v[2:3], v[164:165]
	v_cvt_f32_ubyte0_e32 v0, v163
	v_pk_mul_f32 v[56:57], v[56:57], v[2:3]
	v_rcp_iflag_f32_e32 v2, v0
	v_cvt_f32_ubyte1_e32 v0, v163
	v_rcp_iflag_f32_e32 v3, v0
	v_cvt_f32_ubyte3_e32 v161, v158
	v_cvt_f32_ubyte2_e32 v160, v158
	v_pk_mul_f32 v[156:157], v[156:157], v[160:161]
	v_cvt_f32_ubyte2_e32 v0, v163
	v_pk_mul_f32 v[58:59], v[58:59], v[156:157]
	v_rcp_iflag_f32_e32 v156, v0
	v_cvt_f32_ubyte3_e32 v0, v163
	v_cvt_f32_ubyte1_e32 v163, v159
	v_cvt_f32_ubyte0_e32 v162, v159
	v_rcp_iflag_f32_e32 v157, v0
	v_pk_mul_f32 v[2:3], v[2:3], v[162:163]
	v_cvt_f32_ubyte0_e32 v0, v152
	v_pk_mul_f32 v[52:53], v[52:53], v[2:3]
	v_rcp_iflag_f32_e32 v2, v0
	v_cvt_f32_ubyte1_e32 v0, v152
	v_rcp_iflag_f32_e32 v3, v0
	v_cvt_f32_ubyte3_e32 v161, v159
	v_cvt_f32_ubyte2_e32 v160, v159
	v_pk_mul_f32 v[156:157], v[156:157], v[160:161]
	v_cvt_f32_ubyte2_e32 v0, v152
	v_pk_mul_f32 v[54:55], v[54:55], v[156:157]
	v_rcp_iflag_f32_e32 v156, v0
	v_cvt_f32_ubyte3_e32 v0, v152
	v_cvt_f32_ubyte1_e32 v161, v148
	v_cvt_f32_ubyte0_e32 v160, v148
	v_rcp_iflag_f32_e32 v157, v0
	v_pk_mul_f32 v[2:3], v[2:3], v[160:161]
	v_cvt_f32_ubyte0_e32 v0, v153
	v_pk_mul_f32 v[48:49], v[48:49], v[2:3]
	v_rcp_iflag_f32_e32 v2, v0
	v_cvt_f32_ubyte1_e32 v0, v153
	v_rcp_iflag_f32_e32 v3, v0
	v_cvt_f32_ubyte3_e32 v159, v148
	v_cvt_f32_ubyte2_e32 v158, v148
	v_cvt_f32_ubyte2_e32 v0, v153
	v_pk_mul_f32 v[156:157], v[156:157], v[158:159]
	v_rcp_iflag_f32_e32 v152, v0
	v_cvt_f32_ubyte3_e32 v0, v153
	v_cvt_f32_ubyte1_e32 v159, v149
	v_cvt_f32_ubyte0_e32 v158, v149
	v_rcp_iflag_f32_e32 v153, v0
	v_pk_mul_f32 v[2:3], v[2:3], v[158:159]
	v_cvt_f32_ubyte0_e32 v0, v154
	v_pk_mul_f32 v[44:45], v[44:45], v[2:3]
	v_rcp_iflag_f32_e32 v2, v0
	v_cvt_f32_ubyte1_e32 v0, v154
	v_rcp_iflag_f32_e32 v3, v0
	v_pk_mul_f32 v[50:51], v[50:51], v[156:157]
	v_cvt_f32_ubyte3_e32 v157, v149
	v_cvt_f32_ubyte2_e32 v156, v149
	v_pk_mul_f32 v[148:149], v[152:153], v[156:157]
	v_cvt_f32_ubyte2_e32 v0, v154
	v_pk_mul_f32 v[46:47], v[46:47], v[148:149]
	v_rcp_iflag_f32_e32 v148, v0
	v_cvt_f32_ubyte3_e32 v0, v154
	v_cvt_f32_ubyte1_e32 v157, v150
	v_cvt_f32_ubyte0_e32 v156, v150
	v_rcp_iflag_f32_e32 v149, v0
	v_pk_mul_f32 v[2:3], v[2:3], v[156:157]
	v_cvt_f32_ubyte0_e32 v0, v155
	v_pk_mul_f32 v[40:41], v[40:41], v[2:3]
	v_rcp_iflag_f32_e32 v2, v0
	v_cvt_f32_ubyte1_e32 v0, v155
	v_rcp_iflag_f32_e32 v3, v0
	v_cvt_f32_ubyte3_e32 v153, v150
	v_cvt_f32_ubyte2_e32 v152, v150
	v_pk_mul_f32 v[148:149], v[148:149], v[152:153]
	v_cvt_f32_ubyte2_e32 v0, v155
	v_pk_mul_f32 v[42:43], v[42:43], v[148:149]
	v_rcp_iflag_f32_e32 v148, v0
	v_cvt_f32_ubyte3_e32 v0, v155
; __device__ __forceinline__ float ub0(unsigned w) { return (float)(w & 0xffu); }
; __device__ __forceinline__ float ub1(unsigned w) { return (float)((w >> 8) & 0xffu); }
; __device__ __forceinline__ float ub2(unsigned w) { return (float)((w >> 16) & 0xffu); }
; __device__ __forceinline__ float ub3(unsigned w) { return (float)(w >> 24); }
; __device__ __forceinline__ void gate_ratio4(f32x4& v, unsigned n, unsigned d) {
;     v[0] *= ub0(n) * __builtin_amdgcn_rcpf(ub0(d)); v[1] *= ub1(n) * __builtin_amdgcn_rcpf(ub1(d)); v[2] *= ub2(n) * __builtin_amdgcn_rcpf(ub2(d)); v[3] *= ub3(n) * __builtin_amdgcn_rcpf(ub3(d)); }
;     __device__ __forceinline__ void mid(f32x4 (&acc)[2][2][4][2], const pg8::GUnit& u, int b, int wr, int wc, int fr, int fq) const {
;     ...
;         for (int k = 0; k < 8; ++k) { const int ai = k >> 2, m = k & 3;
;             gate_ratio4(acc[ai][0][m][0], gn[k].x, gd[k].x); gate_ratio4(acc[ai][0][m][1], gn[k].y, gd[k].y); gate_ratio4(acc[ai][1][m][0], gn[k].z, gd[k].z); gate_ratio4(acc[ai][1][m][1], gn[k].w, gd[k].w); }
	v_cvt_f32_ubyte1_e32 v155, v151
	v_cvt_f32_ubyte0_e32 v154, v151
	v_rcp_iflag_f32_e32 v149, v0
	v_pk_mul_f32 v[2:3], v[2:3], v[154:155]
	v_cvt_f32_ubyte0_e32 v0, v144
	v_pk_mul_f32 v[36:37], v[36:37], v[2:3]
	v_rcp_iflag_f32_e32 v2, v0
	v_cvt_f32_ubyte1_e32 v0, v144
	v_rcp_iflag_f32_e32 v3, v0
	v_cvt_f32_ubyte3_e32 v153, v151
	v_cvt_f32_ubyte2_e32 v152, v151
	v_pk_mul_f32 v[148:149], v[148:149], v[152:153]
	v_cvt_f32_ubyte2_e32 v0, v144
	v_pk_mul_f32 v[38:39], v[38:39], v[148:149]
	v_rcp_iflag_f32_e32 v148, v0
	v_cvt_f32_ubyte3_e32 v0, v144
	v_cvt_f32_ubyte1_e32 v153, v140
	v_cvt_f32_ubyte0_e32 v152, v140
	v_rcp_iflag_f32_e32 v149, v0
	v_pk_mul_f32 v[2:3], v[2:3], v[152:153]
	v_cvt_f32_ubyte0_e32 v0, v145
	v_pk_mul_f32 v[32:33], v[32:33], v[2:3]
	v_rcp_iflag_f32_e32 v2, v0
	v_cvt_f32_ubyte1_e32 v0, v145
	v_rcp_iflag_f32_e32 v3, v0
	v_cvt_f32_ubyte3_e32 v151, v140
	v_cvt_f32_ubyte2_e32 v150, v140
	v_cvt_f32_ubyte2_e32 v0, v145
	v_pk_mul_f32 v[148:149], v[148:149], v[150:151]
	v_rcp_iflag_f32_e32 v144, v0
	v_cvt_f32_ubyte3_e32 v0, v145
	v_cvt_f32_ubyte1_e32 v151, v141
	v_cvt_f32_ubyte0_e32 v150, v141
	v_rcp_iflag_f32_e32 v145, v0
	v_pk_mul_f32 v[2:3], v[2:3], v[150:151]
	v_cvt_f32_ubyte0_e32 v0, v146
	v_pk_mul_f32 v[28:29], v[28:29], v[2:3]
	v_rcp_iflag_f32_e32 v2, v0
	v_cvt_f32_ubyte1_e32 v0, v146
	v_rcp_iflag_f32_e32 v3, v0
	v_pk_mul_f32 v[34:35], v[34:35], v[148:149]
	v_cvt_f32_ubyte3_e32 v149, v141
	v_cvt_f32_ubyte2_e32 v148, v141
	v_pk_mul_f32 v[140:141], v[144:145], v[148:149]
	v_cvt_f32_ubyte2_e32 v0, v146
	v_pk_mul_f32 v[30:31], v[30:31], v[140:141]
	v_rcp_iflag_f32_e32 v140, v0
	v_cvt_f32_ubyte3_e32 v0, v146
	v_cvt_f32_ubyte1_e32 v149, v142
	v_cvt_f32_ubyte0_e32 v148, v142
	v_rcp_iflag_f32_e32 v141, v0
	v_pk_mul_f32 v[2:3], v[2:3], v[148:149]
	v_cvt_f32_ubyte0_e32 v0, v147
	v_pk_mul_f32 v[24:25], v[24:25], v[2:3]
	v_rcp_iflag_f32_e32 v2, v0
	v_cvt_f32_ubyte1_e32 v0, v147
	v_rcp_iflag_f32_e32 v3, v0
	v_cvt_f32_ubyte3_e32 v145, v142
	v_cvt_f32_ubyte2_e32 v144, v142
	v_pk_mul_f32 v[140:141], v[140:141], v[144:145]
	v_cvt_f32_ubyte2_e32 v0, v147
	v_pk_mul_f32 v[26:27], v[26:27], v[140:141]
	v_rcp_iflag_f32_e32 v140, v0
	v_cvt_f32_ubyte3_e32 v0, v147
	v_cvt_f32_ubyte1_e32 v147, v143
	v_cvt_f32_ubyte0_e32 v146, v143
	v_rcp_iflag_f32_e32 v141, v0
	v_pk_mul_f32 v[2:3], v[2:3], v[146:147]
	v_cvt_f32_ubyte0_e32 v0, v136
	v_pk_mul_f32 v[20:21], v[20:21], v[2:3]
	v_rcp_iflag_f32_e32 v2, v0
	v_cvt_f32_ubyte1_e32 v0, v136
	v_rcp_iflag_f32_e32 v3, v0
	v_cvt_f32_ubyte3_e32 v145, v143
	v_cvt_f32_ubyte2_e32 v144, v143
	v_pk_mul_f32 v[140:141], v[140:141], v[144:145]
	v_cvt_f32_ubyte2_e32 v0, v136
	v_pk_mul_f32 v[22:23], v[22:23], v[140:141]
	v_rcp_iflag_f32_e32 v140, v0
	v_cvt_f32_ubyte3_e32 v0, v136
	v_cvt_f32_ubyte1_e32 v145, v132
	v_cvt_f32_ubyte0_e32 v144, v132
	v_rcp_iflag_f32_e32 v141, v0
	v_pk_mul_f32 v[2:3], v[2:3], v[144:145]
	v_cvt_f32_ubyte0_e32 v0, v137
	v_pk_mul_f32 v[16:17], v[16:17], v[2:3]
	v_rcp_iflag_f32_e32 v2, v0
	v_cvt_f32_ubyte1_e32 v0, v137
	v_rcp_iflag_f32_e32 v3, v0
	v_cvt_f32_ubyte2_e32 v0, v137
	v_rcp_iflag_f32_e32 v136, v0
	v_cvt_f32_ubyte3_e32 v0, v137
	v_cvt_f32_ubyte3_e32 v143, v132
	v_cvt_f32_ubyte2_e32 v142, v132
	v_rcp_iflag_f32_e32 v137, v0
	v_pk_mul_f32 v[140:141], v[140:141], v[142:143]
	v_cvt_f32_ubyte1_e32 v143, v133
	v_cvt_f32_ubyte0_e32 v142, v133
	v_pk_mul_f32 v[2:3], v[2:3], v[142:143]
	v_cvt_f32_ubyte0_e32 v0, v138
	v_pk_mul_f32 v[18:19], v[18:19], v[140:141]
	v_cvt_f32_ubyte3_e32 v141, v133
	v_cvt_f32_ubyte2_e32 v140, v133
	v_pk_mul_f32 v[12:13], v[12:13], v[2:3]
	v_rcp_iflag_f32_e32 v2, v0
	v_cvt_f32_ubyte1_e32 v0, v138
	v_pk_mul_f32 v[132:133], v[136:137], v[140:141]
	v_rcp_iflag_f32_e32 v3, v0
	v_cvt_f32_ubyte2_e32 v0, v138
	v_pk_mul_f32 v[14:15], v[14:15], v[132:133]
	v_rcp_iflag_f32_e32 v132, v0
	v_cvt_f32_ubyte3_e32 v0, v138
	v_rcp_iflag_f32_e32 v133, v0
	v_cvt_f32_ubyte1_e32 v141, v134
	v_cvt_f32_ubyte0_e32 v140, v134
	v_pk_mul_f32 v[2:3], v[2:3], v[140:141]
	v_cvt_f32_ubyte0_e32 v0, v139
	v_cvt_f32_ubyte3_e32 v137, v134
	v_cvt_f32_ubyte2_e32 v136, v134
	v_pk_mul_f32 v[8:9], v[8:9], v[2:3]
	v_rcp_iflag_f32_e32 v2, v0
	v_cvt_f32_ubyte1_e32 v0, v139
	v_pk_mul_f32 v[132:133], v[132:133], v[136:137]
	v_rcp_iflag_f32_e32 v3, v0
	v_cvt_f32_ubyte2_e32 v0, v139
	v_pk_mul_f32 v[10:11], v[10:11], v[132:133]
	v_rcp_iflag_f32_e32 v132, v0
	v_cvt_f32_ubyte3_e32 v0, v139
	v_rcp_iflag_f32_e32 v133, v0
	v_cvt_f32_ubyte3_e32 v137, v135
	v_cvt_f32_ubyte2_e32 v136, v135
	v_cvt_f32_ubyte1_e32 v139, v135
	v_cvt_f32_ubyte0_e32 v138, v135
	v_pk_mul_f32 v[2:3], v[2:3], v[138:139]
	v_pk_mul_f32 v[132:133], v[132:133], v[136:137]
	v_pk_mul_f32 v[4:5], v[4:5], v[2:3]
	v_pk_mul_f32 v[6:7], v[6:7], v[132:133]
